# v22 + barrier-2 generation poll issued before the pass-B conversion work and consumed after it (acquire only, no poll round trip, before phase 3)
# baseline (speedup 1.0000x reference)
; #define LAS __attribute__((address_space(3)))
; __global__ void __launch_bounds__(512, 2) hymba_fwd(Params p) {
;     ...
;         {
;             const int nfull = (MROWS / 256) * (NPAD / 256) + (MMEM / 256) * (1024 / 256) - ((MROWS / 256) * (NPAD / 256) + (MMEM / 256) * (1024 / 256)) / G * G;
;             const int first_idle = (nfull == 0) ? 0 : nfull, nidle = G - first_idle;
;             if (bx >= first_idle) {
;                 const int lane = tid & 63, wave = __builtin_amdgcn_readfirstlane(tid >> 6);
;                 tr_pipeline(p, (LAS float*)(lds + wave * 16896), lane, (bx - first_idle) * 8 + wave, nidle * 8, NITEMS_P0, NITEMS_ALL);
;                 cache_mem_convert(p, (bx - first_idle) * 512 + tid, nidle * 512);
;             }
.LBB0_458:
	s_cmp_eq_u32 s98, 0
	s_cbranch_scc1 .LBB0_576
	v_mov_b32_e32 v250, 0
	v_readlane_b32 s0, v254, 2
	s_abs_i32 s0, s0
	s_sub_i32 s1, 0, s0
	s_waitcnt vmcnt(0)
	v_cvt_f32_u32_e32 v2, s0
	v_rcp_iflag_f32_e32 v2, v2
	s_nop 0
	v_mul_f32_e32 v2, 0x4f7ffffe, v2
	v_cvt_u32_f32_e32 v2, v2
	s_nop 0
	v_readfirstlane_b32 s2, v2
	s_mul_i32 s1, s1, s2
	s_mul_hi_u32 s1, s2, s1
	s_add_i32 s2, s2, s1
	s_mul_hi_u32 s1, s2, 0x38b
	s_mul_i32 s1, s1, s0
	s_sub_i32 s1, 0x38b, s1
	s_sub_i32 s2, s1, s0
	s_cmp_ge_u32 s1, s0
	s_cselect_b32 s1, s2, s1
	s_sub_i32 s2, s1, s0
	s_cmp_ge_u32 s1, s0
	s_cselect_b32 s2, s2, s1
	s_mov_b32 s2, 0
	s_cmpk_gt_i32 s95, 0x93
	s_cbranch_scc1 .LBB0_576
	s_cmp_lt_i32 s95, s2
	s_cbranch_scc1 .LBB0_576
	v_readlane_b32 s0, v254, 7
	s_lshl_b32 s0, s0, 8
	v_readlane_b32 s4, v254, 5
	v_readlane_b32 s5, v254, 6
	s_add_u32 s0, s4, s0
	s_addc_u32 s1, s5, 0
	v_mov_b32_e32 v250, 0x2400
	s_nop 0
	global_load_dword v250, v250, s[0:1] sc1
	s_nop 1
	v_readfirstlane_b32 s0, v0
	s_sub_i32 s20, s95, s2
	s_lshr_b32 s4, s0, 6
	s_lshl_b32 s0, s20, 3
	v_and_b32_e32 v4, 63, v0
	s_add_i32 s3, s4, s0
	s_cmpk_lt_u32 s3, 0x400
	v_lshrrev_b32_e32 v2, 5, v4
	v_lshrrev_b32_e32 v3, 1, v0
	s_cbranch_scc1 .LBB0_461
	v_and_b32_e32 v140, 0x7c, v166
	v_lshrrev_b32_e32 v141, 5, v4
	v_and_b32_e32 v134, 24, v3
	v_mov_b32_e32 v135, 0
	s_mov_b64 s[0:1], 0
	v_mov_b64_e32 v[136:137], 0
	s_andn2_b64 vcc, exec, s[0:1]
	v_mov_b64_e32 v[4:5], 0
	s_cbranch_vccnz .LBB0_463
	s_branch .LBB0_462

; __device__ __forceinline__ unsigned xb_ld(unsigned* p)              { return __hip_atomic_load(p, __ATOMIC_RELAXED, __HIP_MEMORY_SCOPE_AGENT); }
; #define XB_SPIN(cond, bar) do { unsigned _sp = 0; while (cond) { __builtin_amdgcn_s_sleep(XB_SLEEP); \
;     if ((++_sp & 255u) == 0u) { if (xb_ld(&(bar)[XB_TMO])) break; if (_sp > XB_SPIN_CAP) { atomicAdd(&(bar)[XB_TMO], 1u); break; } } } } while (0)
; __device__ __forceinline__ void xcd_barrier(const XcdBarrier& b) {
;     ...
;         } else {
;             XB_SPIN(xb_ld(&bar[XB_XGEN(b.x)]) == gen, bar);
;             __builtin_amdgcn_fence(__ATOMIC_ACQUIRE, "agent");
;             asm volatile("s_waitcnt vmcnt(0)" ::: "memory");
;         }
.LBB0_576:
	s_cmp_eq_u32 s98, 1
	s_cbranch_scc0 .Lp1_bar
	s_mov_b32 s98, 2
	s_waitcnt vmcnt(0) lgkmcnt(0)
	v_readlane_b32 s0, v254, 9
	s_cmpk_gt_i32 s0, 0x93
	s_cbranch_scc1 .Lb2w_skip
	v_cmp_eq_u32_e32 vcc, 0, v0
	s_and_saveexec_b64 s[0:1], vcc
	s_cbranch_execz .Lb2w_done
	v_readlane_b32 s2, v254, 7
	s_lshl_b32 s2, s2, 8
	v_readlane_b32 s4, v254, 5
	v_readlane_b32 s5, v254, 6
	s_add_u32 s2, s4, s2
	s_addc_u32 s3, s5, 0
	s_mov_b32 s5, 0x8000
	v_mov_b32_e32 v1, 0x2400
	v_readfirstlane_b32 s4, v250
	s_cmp_ge_u32 s4, 2
	s_cbranch_scc1 .Lb2w_ok
